# recurrence producer loop: kernarg re-loads replaced by SGPR copies and the two mid-iteration store-ack waits removed (on top of S=7 + consumer hoist)
# speedup vs baseline: 1.0078x; 1.0006x over previous
; #define LAS __attribute__((address_space(3)))
; __device__ __forceinline__ int opq(int x) { asm volatile("" : "+v"(x)); return x; }
; __device__ __forceinline__ void delta_pre_load(int b, int h, int c, int pt, DeltaPre& dp) {
;     const int bh = b * 8 + h, tt = pt >> 3, d0 = (pt & 7) * 16; const size_t t = (size_t)bh * SEQ + c * 32 + tt;
;     const size_t ro = ((size_t)b * SEQ + c * 32 + tt) * D + h * 128 + d0;
;     const bf16* Kt = (const bf16*)(karg_ws() + WS_Z + 3 * ZB) + ro; const bf16* Qt = (const bf16*)(karg_ws() + WS_H) + ro; const bf16* Vt = (const bf16*)(karg_ws() + WS_Z + 4 * ZB) + ro;
;     dp.k0 = *(const u32x4*)Kt; dp.k1 = *(const u32x4*)(Kt + 8); dp.q0 = *(const u32x4*)Qt; dp.q1 = *(const u32x4*)(Qt + 8); dp.v0 = *(const u32x4*)Vt; dp.v1 = *(const u32x4*)(Vt + 8);
;     const float* GC = (const float*)(karg_ws() + WS_GC);
;     dp.gct = GC[t]; dp.gl = GC[(size_t)bh * SEQ + c * 32 + 31]; dp.bet = ((const float*)(karg_ws() + WS_BETA))[t];
;     dp.nk = ((const float*)((const unsigned char*)karg_out() + OSB_NK))[t]; dp.nq = ((const float*)((const unsigned char*)karg_out() + OSB_NQ))[t];
;     dp.tia = *(const u32x4*)((const bf16*)(karg_ws() + (pt < 128 ? WS_TINV : WS_ATT)) + ((size_t)bh * 64 + c) * 1024 + (pt & 127) * 8);
; }
; __device__ __forceinline__ void delta_rec_stage(LAS unsigned char* buf, int pt, const DeltaPre& dp) {
;     const int tt = pt >> 3, dg = pt & 7, d0 = dg * 16;
;     { LAS bf16* dst = (LAS bf16*)(buf + (pt < 128 ? DR_TI : DR_AT)) + ((pt & 127) >> 2) * 40 + (pt & 3) * 8; *(LAS u32x4*)dst = dp.tia; }
;     if (pt == 0) *(LAS float*)(buf + DR_EGL) = __expf(dp.gl);
; __device__ __forceinline__ void delta_rec_task(const Params& P, LAS unsigned char* lds, int b, int h, int tid) {
;     ...
;     if (producer) {
;         const int pt = opq(tid) - 256;
;         float dn16[16];
; #pragma unroll
;         for (int e = 0; e < 16; ++e) dn16[e] = INP(25)[(pt & 7) * 16 + e];
;         bf16* zgp = (bf16*)(karg_ws() + WS_Z + 5 * ZB) + ((size_t)b * SEQ + (pt >> 3)) * D + h * 128 + (pt & 7) * 16;
;         u32x4 zc0 = {0u, 0u, 0u, 0u}, zc1 = zc0, zn0, zn1;
;     ...
;         for (int c = 0; c < NC; ++c) {
;             if (c > 0) { dcur = dnxt; zc0 = zn0; zc1 = zn1; }
;             if (c + 2 < NC) delta_pre_load(b, h, c + 2, pt, dnxt);
;             zn0 = *(const u32x4*)(zgp + (size_t)c * 32 * D); zn1 = *(const u32x4*)(zgp + (size_t)c * 32 * D + 8);
.LBB0_1835:
	s_load_dwordx2 s[44:45], s[0:1], 0x100
	v_mov_b32_e32 v26, v113
	s_load_dwordx2 s[4:5], s[0:1], 0xc8
	v_lshlrev_b32_e32 v32, 4, v26
	v_and_b32_e32 v27, 0x70, v32
	v_lshlrev_b32_e32 v111, 2, v27
	s_ashr_i32 s13, s12, 31
	s_waitcnt lgkmcnt(0)
	global_load_dword v102, v111, s[4:5]
	s_load_dwordx2 s[4:5], s[0:1], 0xc8
	v_add_u32_e32 v33, 0xffffff00, v26
	v_ashrrev_i32_e32 v22, 3, v33
	v_ashrrev_i32_e32 v23, 31, v22
	s_mov_b64 s[10:11], 0x20000
	s_waitcnt lgkmcnt(0)
	global_load_dword v103, v111, s[4:5] offset:4
	s_load_dwordx2 s[4:5], s[0:1], 0xc8
	s_mov_b64 s[22:23], 0xb100000
	s_mov_b32 s21, 0xb100000
	s_mov_b64 s[24:25], 0x3000000
	s_mov_b32 s38, 0x3000000
	s_waitcnt lgkmcnt(0)
	global_load_dword v100, v111, s[4:5] offset:8
	s_load_dwordx2 s[4:5], s[0:1], 0xc8
	s_mov_b64 s[26:27], 0xd140000
	s_mov_b32 s39, 0xd140000
	v_mov_b32_e32 v21, 0
	v_lshlrev_b64 v[24:25], 11, v[22:23]
	s_waitcnt lgkmcnt(0)
	global_load_dword v101, v111, s[4:5] offset:12
	s_load_dwordx2 s[4:5], s[0:1], 0xc8
	v_lshlrev_b32_e32 v114, 1, v27
	v_mov_b32_e32 v115, v21
	v_mov_b32_e32 v34, 0x7600
	v_mov_b32_e32 v35, 0x6c00
	s_waitcnt lgkmcnt(0)
	global_load_dword v98, v111, s[4:5] offset:16
	s_load_dwordx2 s[4:5], s[0:1], 0xc8
	s_waitcnt lgkmcnt(0)
	global_load_dword v99, v111, s[4:5] offset:20
	s_load_dwordx2 s[4:5], s[0:1], 0xc8
	s_waitcnt lgkmcnt(0)
	global_load_dword v96, v111, s[4:5] offset:24
	s_load_dwordx2 s[4:5], s[0:1], 0xc8
	s_waitcnt lgkmcnt(0)
	global_load_dword v97, v111, s[4:5] offset:28
	s_load_dwordx2 s[4:5], s[0:1], 0xc8
	s_waitcnt lgkmcnt(0)
	global_load_dword v94, v111, s[4:5] offset:32
	s_load_dwordx2 s[4:5], s[0:1], 0xc8
	s_waitcnt lgkmcnt(0)
	global_load_dword v95, v111, s[4:5] offset:36
	s_load_dwordx2 s[4:5], s[0:1], 0xc8
	s_waitcnt lgkmcnt(0)
	global_load_dword v92, v111, s[4:5] offset:40
	s_load_dwordx2 s[4:5], s[0:1], 0xc8
	s_waitcnt lgkmcnt(0)
	global_load_dword v93, v111, s[4:5] offset:44
	s_load_dwordx2 s[4:5], s[0:1], 0xc8
	s_waitcnt lgkmcnt(0)
	global_load_dword v104, v111, s[4:5] offset:48
	s_load_dwordx2 s[4:5], s[0:1], 0xc8
	s_waitcnt lgkmcnt(0)
	global_load_dword v105, v111, s[4:5] offset:52
	s_load_dwordx2 s[4:5], s[0:1], 0xc8
	s_waitcnt lgkmcnt(0)
	global_load_dword v106, v111, s[4:5] offset:56
	s_load_dwordx2 s[14:15], s[0:1], 0xc8
	s_lshl_b64 s[4:5], s[12:13], 22
	s_waitcnt lgkmcnt(0)
	global_load_dword v107, v111, s[14:15] offset:60
	s_load_dwordx2 s[16:17], s[0:1], 0x108
	s_load_dwordx2 s[28:29], s[0:1], 0x108
	s_load_dwordx2 s[30:31], s[0:1], 0x108
	s_load_dwordx2 s[34:35], s[0:1], 0x108
	s_mov_b32 s15, 0
	s_waitcnt lgkmcnt(0)
	s_add_u32 s36, s16, s4
	s_addc_u32 s37, s17, s5
	s_lshl_b64 s[12:13], s[12:13], 11
	s_lshl_b32 s20, s18, 7
	v_lshl_add_u64 v[0:1], s[12:13], 0, v[22:23]
	v_or_b32_e32 v2, s20, v27
	v_lshlrev_b64 v[0:1], 11, v[0:1]
	v_lshl_or_b32 v0, v2, 1, v0
	v_lshl_add_u64 v[0:1], v[0:1], 0, s[10:11]
	v_lshl_add_u64 v[2:3], s[28:29], 0, v[0:1]
	v_lshl_add_u64 v[6:7], v[2:3], 0, s[22:23]
	v_add_co_u32_e32 v2, vcc, s21, v2
	v_lshl_add_u64 v[4:5], s[30:31], 0, v[0:1]
	s_nop 0
	v_addc_co_u32_e32 v3, vcc, 0, v3, vcc
	v_lshl_add_u64 v[8:9], v[4:5], 0, s[24:25]
	v_add_co_u32_e32 v4, vcc, s38, v4
	v_lshl_add_u64 v[0:1], s[34:35], 0, v[0:1]
	s_nop 0
	v_addc_co_u32_e32 v5, vcc, 0, v5, vcc
	v_lshl_add_u64 v[10:11], v[0:1], 0, s[26:27]
	v_add_co_u32_e32 v0, vcc, s39, v0
	s_ashr_i32 s3, s2, 31
	s_nop 0
	v_addc_co_u32_e32 v1, vcc, 0, v1, vcc
	global_load_dwordx4 v[48:51], v[2:3], off
	global_load_dwordx4 v[44:47], v[6:7], off offset:16
	global_load_dwordx4 v[36:39], v[4:5], off
	global_load_dwordx4 v[28:31], v[8:9], off offset:16
	global_load_dwordx4 v[16:19], v[0:1], off
	global_load_dwordx4 v[12:15], v[10:11], off offset:16
	s_load_dwordx2 s[10:11], s[0:1], 0x108
	s_lshl_b32 s14, s18, 8
	s_lshl_b64 s[18:19], s[2:3], 11
	s_lshl_b64 s[12:13], s[2:3], 17
	s_or_b32 s18, s18, 64
	v_lshl_add_u64 v[0:1], s[18:19], 0, v[22:23]
	s_waitcnt lgkmcnt(0)
	s_add_u32 s10, s10, 0x2880000
	v_lshlrev_b64 v[0:1], 2, v[0:1]
	s_addc_u32 s11, s11, 0
	s_lshl_b64 s[18:19], s[18:19], 2
	v_lshl_add_u64 v[2:3], s[10:11], 0, v[0:1]
	s_add_u32 s10, s10, s18
	s_addc_u32 s11, s11, s19
	global_load_dword v123, v[2:3], off
	global_load_dword v124, v21, s[10:11] offset:124
	s_load_dwordx2 s[10:11], s[0:1], 0x108
	s_mov_b32 s28, 0x2f10000
	v_lshl_add_u64 v[2:3], s[36:37], 0, v[24:25]
	v_lshl_add_u64 v[2:3], v[2:3], 0, s[14:15]
	s_mov_b32 s29, 0x8a68000
	s_waitcnt lgkmcnt(0)
	v_lshl_add_u64 v[4:5], s[10:11], 0, v[0:1]
	v_add_co_u32_e32 v4, vcc, s28, v4
	s_mov_b32 s30, 0x8ae8000
	s_nop 0
	v_addc_co_u32_e32 v5, vcc, 0, v5, vcc
	global_load_dword v116, v[4:5], off
	s_load_dwordx2 s[10:11], s[0:1], 0x100
	v_lshl_add_u64 v[4:5], v[2:3], 0, v[114:115]
	s_mov_b64 s[18:19], 0xf180000
	v_lshl_add_u64 v[108:109], v[4:5], 0, s[18:19]
	s_movk_i32 s21, 0x180
	s_waitcnt lgkmcnt(0)
	v_lshl_add_u64 v[2:3], s[10:11], 0, v[0:1]
	v_add_co_u32_e32 v2, vcc, s29, v2
	s_mov_b32 s31, 0xf180000
	s_nop 0
	v_addc_co_u32_e32 v3, vcc, 0, v3, vcc
	global_load_dword v125, v[2:3], off
	s_load_dwordx2 s[10:11], s[0:1], 0x100
	v_and_b32_e32 v2, 0x7f0, v32
	v_mov_b32_e32 v3, v21
	v_lshlrev_b32_e32 v32, 3, v26
	v_and_b32_e32 v32, 24, v32
	s_waitcnt lgkmcnt(0)
	v_lshl_add_u64 v[0:1], s[10:11], 0, v[0:1]
	v_add_co_u32_e32 v0, vcc, s30, v0
	v_cmp_gt_i32_e64 s[10:11], s21, v26
	s_nop 0
	v_addc_co_u32_e32 v1, vcc, 0, v1, vcc
	global_load_dword v126, v[0:1], off
	s_load_dwordx2 s[18:19], s[0:1], 0x108
	v_mov_b32_e32 v0, 0x1980000
	v_mov_b32_e32 v1, 0x1180000
	v_cndmask_b32_e64 v20, v0, v1, s[10:11]
	v_cndmask_b32_e64 v115, v34, v35, s[10:11]
	s_waitcnt lgkmcnt(0)
	v_lshl_add_u64 v[0:1], s[18:19], 0, v[20:21]
	v_lshl_add_u64 v[0:1], v[0:1], 0, s[12:13]
	v_lshl_add_u64 v[0:1], v[0:1], 0, v[2:3]
	s_movk_i32 s18, 0x1000
	v_add_co_u32_e32 v0, vcc, s18, v0
	v_bfe_u32 v34, v26, 2, 5
	s_nop 0
	v_addc_co_u32_e32 v1, vcc, 0, v1, vcc
	v_add_co_u32_e32 v4, vcc, 0xf180000, v4
	global_load_dwordx4 v[0:3], v[0:1], off
	s_nop 0
	v_addc_co_u32_e32 v5, vcc, 0, v5, vcc
	global_load_dwordx4 v[8:11], v[4:5], off
	s_nop 0
	global_load_dwordx4 v[4:7], v[108:109], off offset:16
	v_mul_u32_u24_e32 v121, 0x50, v34
	v_cmp_eq_u32_e64 s[10:11], 0, v33
	v_add_u32_e32 v33, 0, v115
	v_lshlrev_b32_e32 v122, 1, v32
	v_add3_u32 v32, v33, v121, v122
	s_waitcnt vmcnt(30)
	ds_write_b128 v32, v[88:91] offset:49680
	s_and_saveexec_b64 s[18:19], s[10:11]
	s_cbranch_execz .LBB0_1837
	v_mul_f32_e32 v32, 0x3fb8aa3b, v118
	v_exp_f32_e32 v32, v32
	s_add_i32 s21, 0, 0x18410
	v_mov_b32_e32 v33, s21
	ds_write_b32 v33, v32

; __device__ __forceinline__ float* karg_out() { return *(volatile KAS fptr_t*)((const KAS char*)__builtin_amdgcn_kernarg_segment_ptr() + 256); }
; __device__ __forceinline__ unsigned char* karg_ws() { return *(volatile KAS ucptr_t*)((const KAS char*)__builtin_amdgcn_kernarg_segment_ptr() + 264); }
; __device__ __forceinline__ void delta_pre_load(int b, int h, int c, int pt, DeltaPre& dp) {
;     const int bh = b * 8 + h, tt = pt >> 3, d0 = (pt & 7) * 16; const size_t t = (size_t)bh * SEQ + c * 32 + tt;
;     const size_t ro = ((size_t)b * SEQ + c * 32 + tt) * D + h * 128 + d0;
;     const bf16* Kt = (const bf16*)(karg_ws() + WS_Z + 3 * ZB) + ro; const bf16* Qt = (const bf16*)(karg_ws() + WS_H) + ro; const bf16* Vt = (const bf16*)(karg_ws() + WS_Z + 4 * ZB) + ro;
;     dp.k0 = *(const u32x4*)Kt; dp.k1 = *(const u32x4*)(Kt + 8); dp.q0 = *(const u32x4*)Qt; dp.q1 = *(const u32x4*)(Qt + 8); dp.v0 = *(const u32x4*)Vt; dp.v1 = *(const u32x4*)(Vt + 8);
;     const float* GC = (const float*)(karg_ws() + WS_GC);
;     dp.gct = GC[t]; dp.gl = GC[(size_t)bh * SEQ + c * 32 + 31]; dp.bet = ((const float*)(karg_ws() + WS_BETA))[t];
;     dp.nk = ((const float*)((const unsigned char*)karg_out() + OSB_NK))[t]; dp.nq = ((const float*)((const unsigned char*)karg_out() + OSB_NQ))[t];
;     dp.tia = *(const u32x4*)((const bf16*)(karg_ws() + (pt < 128 ? WS_TINV : WS_ATT)) + ((size_t)bh * 64 + c) * 1024 + (pt & 127) * 8);
; __device__ __forceinline__ void delta_rec_task(const Params& P, LAS unsigned char* lds, int b, int h, int tid) {
;     ...
;         for (int c = 0; c < NC; ++c) {
;             if (c > 0) { dcur = dnxt; zc0 = zn0; zc1 = zn1; }
;             if (c + 2 < NC) delta_pre_load(b, h, c + 2, pt, dnxt);
;             zn0 = *(const u32x4*)(zgp + (size_t)c * 32 * D); zn1 = *(const u32x4*)(zgp + (size_t)c * 32 * D + 8);
.LBB0_1838:
	s_mov_b64 s[26:27], s[76:77]
	s_mov_b64 s[38:39], s[76:77]
	s_mov_b64 s[40:41], s[76:77]
	v_lshl_add_u64 v[78:79], v[76:77], 0, s[12:13]
	s_waitcnt vmcnt(2)
	v_mov_b64_e32 v[130:131], v[2:3]
	s_waitcnt lgkmcnt(0)
	v_lshl_add_u64 v[20:21], s[26:27], 0, v[72:73]
	v_lshl_add_u64 v[20:21], v[20:21], 0, s[12:13]
	v_lshl_add_u64 v[22:23], s[38:39], 0, v[72:73]
	v_lshl_add_u64 v[24:25], v[20:21], 0, s[16:17]
	v_add_co_u32_e32 v20, vcc, s3, v20
	v_lshl_add_u64 v[22:23], v[22:23], 0, s[12:13]
	s_nop 0
	v_addc_co_u32_e32 v21, vcc, 0, v21, vcc
	v_lshl_add_u64 v[32:33], s[40:41], 0, v[72:73]
	global_load_dwordx4 v[64:67], v[20:21], off
	global_load_dwordx4 v[60:63], v[24:25], off offset:16
	v_add_co_u32_e32 v20, vcc, s14, v22
	v_lshl_add_u64 v[32:33], v[32:33], 0, s[12:13]
	s_nop 0
	v_addc_co_u32_e32 v21, vcc, 0, v23, vcc
	v_lshl_add_u64 v[26:27], v[22:23], 0, s[18:19]
	global_load_dwordx4 v[56:59], v[20:21], off
	global_load_dwordx4 v[52:55], v[26:27], off offset:16
	v_add_co_u32_e32 v20, vcc, s34, v32
	v_lshl_add_u64 v[34:35], v[32:33], 0, s[20:21]
	s_nop 0
	v_addc_co_u32_e32 v21, vcc, 0, v33, vcc
	global_load_dwordx4 v[40:43], v[20:21], off
	s_nop 0
	global_load_dwordx4 v[32:35], v[34:35], off offset:16
	s_mov_b64 s[26:27], s[76:77]
	v_mov_b64_e32 v[128:129], v[0:1]
	s_waitcnt lgkmcnt(0)
	v_lshl_add_u64 v[20:21], s[26:27], 0, v[74:75]
	v_lshl_add_u64 v[20:21], v[20:21], 0, s[4:5]
	v_add_co_u32_e32 v20, vcc, s35, v20
	s_add_u32 s26, s26, s4
	s_nop 0
	v_addc_co_u32_e32 v21, vcc, 0, v21, vcc
	s_addc_u32 s27, s27, s5
	global_load_dword v84, v[20:21], off offset:384
	global_load_dword v85, v69, s[26:27] offset:508
	s_mov_b64 s[26:27], s[76:77]
	s_bitcmp1_b32 s36, 0
	s_waitcnt lgkmcnt(0)
	v_lshl_add_u64 v[20:21], s[26:27], 0, v[74:75]
	v_lshl_add_u64 v[20:21], v[20:21], 0, s[4:5]
	v_add_co_u32_e32 v20, vcc, s28, v20
	s_nop 1
	v_addc_co_u32_e32 v21, vcc, 0, v21, vcc
	global_load_dword v68, v[20:21], off offset:384
	s_mov_b64 s[26:27], s[44:45]
	s_waitcnt lgkmcnt(0)
	v_lshl_add_u64 v[20:21], s[26:27], 0, v[74:75]
	v_lshl_add_u64 v[20:21], v[20:21], 0, s[4:5]
	v_add_co_u32_e32 v20, vcc, s29, v20
	s_nop 1
	v_addc_co_u32_e32 v21, vcc, 0, v21, vcc
	global_load_dword v86, v[20:21], off offset:384
	s_mov_b64 s[26:27], s[44:45]
	s_waitcnt lgkmcnt(0)
	v_lshl_add_u64 v[20:21], s[26:27], 0, v[74:75]
	v_lshl_add_u64 v[20:21], v[20:21], 0, s[4:5]
	v_add_co_u32_e32 v20, vcc, s30, v20
	s_nop 1
	v_addc_co_u32_e32 v21, vcc, 0, v21, vcc
	global_load_dword v87, v[20:21], off offset:384
	s_mov_b64 s[26:27], s[76:77]
	v_add_co_u32_e32 v22, vcc, 0xf190000, v78
	v_lshl_add_u64 v[20:21], v[78:79], 0, s[22:23]
	s_nop 0
	v_addc_co_u32_e32 v23, vcc, 0, v79, vcc
	s_waitcnt lgkmcnt(0)
	v_lshl_add_u64 v[0:1], s[26:27], 0, v[70:71]
	global_load_dwordx4 v[0:3], v[0:1], off
	s_nop 0
	global_load_dwordx4 v[24:27], v[22:23], off
	s_nop 0
	global_load_dwordx4 v[20:23], v[20:21], off offset:16
	s_cselect_b32 s26, 0xc210, 0
	s_add_i32 s37, s26, 0
	v_add_u32_e32 v110, s37, v115
	v_add3_u32 v110, v110, v121, v122
	ds_write_b128 v110, v[128:131]
	s_and_saveexec_b64 s[26:27], s[10:11]
	s_cbranch_execz .LBB0_1840
	v_mul_f32_e32 v110, 0x3fb8aa3b, v124
	v_exp_f32_e32 v110, v110
	v_mov_b32_e32 v117, s37
	ds_write_b32 v117, v110 offset:49664
